# merge GEMM gate math: counted vmcnt waits so the next gate rows stay in flight (was vmcnt(0) right after issuing loads)
# baseline (speedup 1.0000x reference)
.LBB0_686:
	s_cmp_lg_u32 s68, 8
	s_cbranch_scc1 .LBB0_678
	v_mov_b32_e32 v1, v194
	v_mov_b32_e32 v3, v195
	s_mov_b32 s3, 0x10000
	v_add_u32_e32 v2, s51, v1
	v_lshl_add_u32 v132, v3, 3, s93
	v_ashrrev_i32_e32 v133, 31, v132
	v_ashrrev_i32_e32 v3, 31, v2
	v_lshl_add_u64 v[132:133], v[132:133], 1, s[30:31]
	v_lshlrev_b64 v[2:3], 12, v[2:3]
	v_lshl_add_u64 v[2:3], v[132:133], 0, v[2:3]
	global_load_dwordx4 v[198:201], v[2:3], off
	global_load_dwordx4 v[202:205], v[2:3], off offset:2048
	global_load_dwordx4 v[206:209], v[2:3], off offset:256
	global_load_dwordx4 v[210:213], v[2:3], off offset:2304
	v_add_co_u32_e32 v134, vcc, s3, v2
	v_lshl_add_u64 v[132:133], v[2:3], 0, s[26:27]
	s_nop 0
	v_addc_co_u32_e32 v135, vcc, 0, v3, vcc
	s_mov_b64 vcc, 0x20000
	s_nop 0
	v_lshl_add_u64 v[136:137], v[2:3], 0, vcc
	v_add_co_u32_e32 v138, vcc, s84, v2
	v_lshl_add_u64 v[214:215], v[2:3], 0, s[40:41]
	s_nop 0
	v_addc_co_u32_e32 v139, vcc, 0, v3, vcc
	v_add_co_u32_e32 v144, vcc, s85, v2
	v_addc_co_u32_e32 v145, vcc, 0, v3, vcc
	global_load_dwordx4 v[172:175], v[132:133], off offset:2048
	global_load_dwordx4 v[168:171], v[132:133], off offset:256
	global_load_dwordx4 v[176:179], v[134:135], off
	global_load_dwordx4 v[164:167], v[132:133], off offset:2304
	global_load_dwordx4 v[156:159], v[136:137], off offset:2048
	global_load_dwordx4 v[152:155], v[136:137], off offset:256
	global_load_dwordx4 v[160:163], v[138:139], off
	global_load_dwordx4 v[148:151], v[136:137], off offset:2304
	global_load_dwordx4 v[140:143], v[214:215], off offset:2048
	s_nop 0
	global_load_dwordx4 v[136:139], v[214:215], off offset:256
	s_nop 0
	global_load_dwordx4 v[144:147], v[144:145], off
	s_nop 0
	global_load_dwordx4 v[132:135], v[214:215], off offset:2304
	s_waitcnt vmcnt(12)
	v_lshlrev_b32_e32 v1, 16, v198
	v_and_b32_e32 v198, 0xffff0000, v198
	v_lshlrev_b32_e32 v214, 16, v199
	v_and_b32_e32 v215, 0xffff0000, v199
	v_lshlrev_b32_e32 v199, 16, v200
	v_and_b32_e32 v200, 0xffff0000, v200
	v_lshlrev_b32_e32 v216, 16, v201
	v_and_b32_e32 v219, 0xffff0000, v201
	v_lshlrev_b32_e32 v201, 16, v202
	v_and_b32_e32 v202, 0xffff0000, v202
	v_lshlrev_b32_e32 v217, 16, v203
	v_and_b32_e32 v220, 0xffff0000, v203
	v_lshlrev_b32_e32 v203, 16, v204
	v_mul_f32_e32 v1, 0xbfb8aa3b, v1
	v_mul_f32_e32 v199, 0xbfb8aa3b, v199
	v_max_f32_e64 v203, -v203, -v203
	v_mul_f32_e32 v198, 0xbfb8aa3b, v198
	v_max_f32_e64 v202, -v202, -v202
	v_mul_f32_e32 v200, 0xbfb8aa3b, v200
	v_exp_f32_e32 v1, v1
	v_lshlrev_b32_e32 v221, 16, v205
	v_and_b32_e32 v222, 0xffff0000, v205
	v_mul_f32_e32 v205, 0xbfb8aa3b, v214
	v_exp_f32_e32 v214, v199
	v_min_f32_e32 v199, 0x42a00000, v203
	v_exp_f32_e32 v203, v198
	v_min_f32_e32 v198, 0x42a00000, v202
	v_exp_f32_e32 v202, v200
	v_and_b32_e32 v204, 0xffff0000, v204
	v_max_f32_e64 v204, -v204, -v204
	v_min_f32_e32 v200, 0x42a00000, v204
	v_exp_f32_e32 v204, v205
	v_mul_f32_e32 v199, 0x3fb8aa3b, v199
	v_mul_f32_e32 v205, 0x3fb8aa3b, v198
	v_add_f32_e32 v1, 1.0, v1
	v_mul_f32_e32 v216, 0xbfb8aa3b, v216
	v_mul_f32_e32 v218, 0x3fb8aa3b, v200
	v_exp_f32_e32 v200, v199
	v_exp_f32_e32 v199, v205
	v_add_f32_e32 v205, 1.0, v214
	v_add_f32_e32 v214, 1.0, v202
	v_rcp_f32_e32 v202, v1
	v_max_f32_e64 v1, -v217, -v217
	v_exp_f32_e32 v217, v216
	v_max_f32_e64 v201, -v201, -v201
	v_min_f32_e32 v201, 0x42a00000, v201
	v_min_f32_e32 v1, 0x42a00000, v1
	v_mul_f32_e32 v201, 0x3fb8aa3b, v201
	v_mul_f32_e32 v1, 0x3fb8aa3b, v1
	v_mul_f32_e32 v215, 0xbfb8aa3b, v215
	v_exp_f32_e32 v198, v201
	v_exp_f32_e32 v201, v218
	v_add_f32_e32 v218, 1.0, v204
	v_exp_f32_e32 v216, v1
	v_add_f32_e32 v1, 1.0, v217
	v_exp_f32_e32 v215, v215
	v_rcp_f32_e32 v204, v205
	v_rcp_f32_e32 v205, v214
	v_rcp_f32_e32 v214, v218
	v_rcp_f32_e32 v218, v1
	v_max_f32_e64 v1, -v221, -v221
	v_max_f32_e64 v217, -v220, -v220
	v_min_f32_e32 v1, 0x42a00000, v1
	v_min_f32_e32 v217, 0x42a00000, v217
	v_mul_f32_e32 v1, 0x3fb8aa3b, v1
	v_mul_f32_e32 v217, 0x3fb8aa3b, v217
	v_add_f32_e32 v203, 1.0, v203
	v_exp_f32_e32 v217, v217
	v_exp_f32_e32 v220, v1
	v_add_f32_e32 v1, 1.0, v215
	v_rcp_f32_e32 v203, v203
	v_rcp_f32_e32 v215, v1
	v_mul_f32_e32 v1, 0xbfb8aa3b, v219
	v_exp_f32_e32 v1, v1
	v_pk_add_f32 v[216:217], v[216:217], 1.0 op_sel_hi:[1,0]
	v_pk_add_f32 v[198:199], v[198:199], 1.0 op_sel_hi:[1,0]
	v_pk_add_f32 v[200:201], v[200:201], 1.0 op_sel_hi:[1,0]
	v_pk_mul_f32 v[198:199], v[202:203], v[198:199]
	v_pk_mul_f32 v[202:203], v[214:215], v[216:217]
	v_add_f32_e32 v1, 1.0, v1
	v_pk_mul_f32 v[126:127], v[126:127], v[202:203]
	v_max_f32_e64 v202, -v222, -v222
	v_min_f32_e32 v202, 0x42a00000, v202
	v_mul_f32_e32 v202, 0x3fb8aa3b, v202
	v_rcp_f32_e32 v219, v1
	v_lshlrev_b32_e32 v1, 16, v206
	v_exp_f32_e32 v221, v202
	v_mul_f32_e32 v1, 0xbfb8aa3b, v1
	v_exp_f32_e32 v1, v1
	v_pk_mul_f32 v[200:201], v[204:205], v[200:201]
	v_pk_mul_f32 v[124:125], v[124:125], v[198:199]
	v_pk_add_f32 v[198:199], v[220:221], 1.0 op_sel_hi:[1,0]
	v_pk_mul_f32 v[128:129], v[128:129], v[200:201]
	v_lshlrev_b32_e32 v200, 16, v208
	v_pk_mul_f32 v[198:199], v[218:219], v[198:199]
	v_lshlrev_b32_e32 v202, 16, v210
	v_add_f32_e32 v1, 1.0, v1
	v_mul_f32_e32 v200, 0xbfb8aa3b, v200
	v_pk_mul_f32 v[130:131], v[130:131], v[198:199]
	v_rcp_f32_e32 v198, v1
	v_max_f32_e64 v1, -v202, -v202
	v_exp_f32_e32 v202, v200
	v_and_b32_e32 v199, 0xffff0000, v206
	v_min_f32_e32 v1, 0x42a00000, v1
	v_mul_f32_e32 v1, 0x3fb8aa3b, v1
	v_mul_f32_e32 v199, 0xbfb8aa3b, v199
	v_lshlrev_b32_e32 v204, 16, v212
	v_exp_f32_e32 v200, v1
	v_add_f32_e32 v1, 1.0, v202
	v_exp_f32_e32 v199, v199
	v_rcp_f32_e32 v202, v1
	v_max_f32_e64 v1, -v204, -v204
	v_min_f32_e32 v1, 0x42a00000, v1
	v_and_b32_e32 v201, 0xffff0000, v208
	v_mul_f32_e32 v1, 0x3fb8aa3b, v1
	v_and_b32_e32 v203, 0xffff0000, v210
	v_exp_f32_e32 v204, v1
	v_add_f32_e32 v1, 1.0, v199
	v_mul_f32_e32 v201, 0xbfb8aa3b, v201
	v_rcp_f32_e32 v199, v1
	v_max_f32_e64 v1, -v203, -v203
	v_exp_f32_e32 v203, v201
	v_min_f32_e32 v1, 0x42a00000, v1
	v_lshlrev_b32_e32 v205, 16, v207
	v_mul_f32_e32 v1, 0x3fb8aa3b, v1
	v_and_b32_e32 v206, 0xffff0000, v212
	v_exp_f32_e32 v201, v1
	v_add_f32_e32 v1, 1.0, v203
	v_mul_f32_e32 v205, 0xbfb8aa3b, v205
	v_rcp_f32_e32 v203, v1
	v_max_f32_e64 v1, -v206, -v206
	v_exp_f32_e32 v206, v205
	v_min_f32_e32 v1, 0x42a00000, v1
	v_lshlrev_b32_e32 v208, 16, v209
	v_mul_f32_e32 v1, 0x3fb8aa3b, v1
	v_and_b32_e32 v214, 0xffff0000, v209
	v_lshlrev_b32_e32 v209, 16, v211
	v_exp_f32_e32 v205, v1
	v_add_f32_e32 v1, 1.0, v206
	v_mul_f32_e32 v208, 0xbfb8aa3b, v208
	v_rcp_f32_e32 v206, v1
	v_max_f32_e64 v1, -v209, -v209
	v_exp_f32_e32 v209, v208
	v_and_b32_e32 v207, 0xffff0000, v207
	v_min_f32_e32 v1, 0x42a00000, v1
	v_mul_f32_e32 v1, 0x3fb8aa3b, v1
	v_mul_f32_e32 v207, 0xbfb8aa3b, v207
	v_and_b32_e32 v211, 0xffff0000, v211
	v_lshlrev_b32_e32 v212, 16, v213
	v_exp_f32_e32 v208, v1
	v_add_f32_e32 v1, 1.0, v209
	v_exp_f32_e32 v207, v207
	v_rcp_f32_e32 v210, v1
	v_max_f32_e64 v1, -v212, -v212
	v_max_f32_e64 v209, -v211, -v211
	v_min_f32_e32 v1, 0x42a00000, v1
	v_min_f32_e32 v209, 0x42a00000, v209
	v_mul_f32_e32 v1, 0x3fb8aa3b, v1
	v_mul_f32_e32 v209, 0x3fb8aa3b, v209
	v_exp_f32_e32 v209, v209
	v_exp_f32_e32 v212, v1
	v_add_f32_e32 v1, 1.0, v207
	v_rcp_f32_e32 v207, v1
	v_pk_add_f32 v[208:209], v[208:209], 1.0 op_sel_hi:[1,0]
	v_pk_add_f32 v[200:201], v[200:201], 1.0 op_sel_hi:[1,0]
	v_mul_f32_e32 v1, 0xbfb8aa3b, v214
	v_and_b32_e32 v213, 0xffff0000, v213
	v_pk_mul_f32 v[198:199], v[198:199], v[200:201]
	v_pk_mul_f32 v[200:201], v[206:207], v[208:209]
	v_exp_f32_e32 v1, v1
	v_pk_mul_f32 v[118:119], v[118:119], v[200:201]
	v_max_f32_e64 v200, -v213, -v213
	v_min_f32_e32 v200, 0x42a00000, v200
	v_mul_f32_e32 v200, 0x3fb8aa3b, v200
	v_exp_f32_e32 v213, v200
	v_add_f32_e32 v1, 1.0, v1
	v_rcp_f32_e32 v211, v1
	s_waitcnt vmcnt(0)
	v_lshlrev_b32_e32 v1, 16, v176
	v_mul_f32_e32 v1, 0xbfb8aa3b, v1
	v_pk_mul_f32 v[116:117], v[116:117], v[198:199]
	v_pk_add_f32 v[198:199], v[212:213], 1.0 op_sel_hi:[1,0]
	v_exp_f32_e32 v1, v1
	v_pk_mul_f32 v[198:199], v[210:211], v[198:199]
	v_pk_add_f32 v[200:201], v[204:205], 1.0 op_sel_hi:[1,0]
	v_pk_mul_f32 v[122:123], v[122:123], v[198:199]
	v_and_b32_e32 v198, 0xffff0000, v176
	v_lshlrev_b32_e32 v176, 16, v178
	v_pk_mul_f32 v[200:201], v[202:203], v[200:201]
	v_lshlrev_b32_e32 v202, 16, v173
	v_and_b32_e32 v204, 0xffff0000, v173
	v_lshlrev_b32_e32 v173, 16, v174
	v_and_b32_e32 v205, 0xffff0000, v174
	v_mul_f32_e32 v174, 0xbfb8aa3b, v176
	v_pk_mul_f32 v[120:121], v[120:121], v[200:201]
	v_lshlrev_b32_e32 v199, 16, v177
	v_and_b32_e32 v201, 0xffff0000, v177
	v_and_b32_e32 v177, 0xffff0000, v178
	v_lshlrev_b32_e32 v178, 16, v172
	v_lshlrev_b32_e32 v206, 16, v175
	v_and_b32_e32 v207, 0xffff0000, v175
	v_add_f32_e32 v1, 1.0, v1
	v_exp_f32_e32 v175, v174
	v_lshlrev_b32_e32 v200, 16, v179
	v_and_b32_e32 v203, 0xffff0000, v179
	v_and_b32_e32 v179, 0xffff0000, v172
	v_rcp_f32_e32 v172, v1
	v_max_f32_e64 v1, -v178, -v178
	v_min_f32_e32 v1, 0x42a00000, v1
	v_mul_f32_e32 v1, 0x3fb8aa3b, v1
	v_exp_f32_e32 v174, v1
	v_add_f32_e32 v1, 1.0, v175
	v_rcp_f32_e32 v176, v1
	v_max_f32_e64 v1, -v173, -v173
	v_mul_f32_e32 v173, 0xbfb8aa3b, v198
	v_exp_f32_e32 v173, v173
	v_min_f32_e32 v1, 0x42a00000, v1
	v_mul_f32_e32 v1, 0x3fb8aa3b, v1
	v_mul_f32_e32 v175, 0xbfb8aa3b, v177
	v_exp_f32_e32 v178, v1
	v_add_f32_e32 v1, 1.0, v173
	v_exp_f32_e32 v177, v175
	v_rcp_f32_e32 v173, v1
	v_max_f32_e64 v1, -v179, -v179
	v_min_f32_e32 v1, 0x42a00000, v1
	v_mul_f32_e32 v1, 0x3fb8aa3b, v1
	v_mul_f32_e32 v179, 0xbfb8aa3b, v199
	v_exp_f32_e32 v175, v1
	v_add_f32_e32 v1, 1.0, v177
	v_exp_f32_e32 v198, v179
	v_rcp_f32_e32 v177, v1
	v_max_f32_e64 v1, -v205, -v205
	v_min_f32_e32 v1, 0x42a00000, v1
	v_mul_f32_e32 v1, 0x3fb8aa3b, v1
	v_mul_f32_e32 v199, 0xbfb8aa3b, v200
	v_exp_f32_e32 v179, v1
	v_add_f32_e32 v1, 1.0, v198
	v_exp_f32_e32 v199, v199
	v_rcp_f32_e32 v198, v1
	v_max_f32_e64 v1, -v202, -v202
	v_min_f32_e32 v1, 0x42a00000, v1
	v_mul_f32_e32 v1, 0x3fb8aa3b, v1
	v_exp_f32_e32 v200, v1
	v_add_f32_e32 v1, 1.0, v199
	v_mul_f32_e32 v199, 0xbfb8aa3b, v201
	v_exp_f32_e32 v199, v199
	v_rcp_f32_e32 v202, v1
	v_max_f32_e64 v1, -v206, -v206
	v_max_f32_e64 v201, -v204, -v204
	v_min_f32_e32 v1, 0x42a00000, v1
	v_min_f32_e32 v201, 0x42a00000, v201
	v_mul_f32_e32 v1, 0x3fb8aa3b, v1
	v_mul_f32_e32 v201, 0x3fb8aa3b, v201
	v_exp_f32_e32 v201, v201
	v_exp_f32_e32 v204, v1
	v_add_f32_e32 v1, 1.0, v199
	v_rcp_f32_e32 v199, v1
	v_pk_add_f32 v[200:201], v[200:201], 1.0 op_sel_hi:[1,0]
	v_pk_add_f32 v[174:175], v[174:175], 1.0 op_sel_hi:[1,0]
	v_mul_f32_e32 v1, 0xbfb8aa3b, v203
	v_pk_mul_f32 v[172:173], v[172:173], v[174:175]
	v_pk_mul_f32 v[174:175], v[198:199], v[200:201]
	v_exp_f32_e32 v1, v1
	v_pk_mul_f32 v[110:111], v[110:111], v[174:175]
	v_max_f32_e64 v174, -v207, -v207
	v_min_f32_e32 v174, 0x42a00000, v174
	v_mul_f32_e32 v174, 0x3fb8aa3b, v174
	v_exp_f32_e32 v205, v174
	v_add_f32_e32 v1, 1.0, v1
	v_rcp_f32_e32 v203, v1
	v_lshlrev_b32_e32 v1, 16, v168
	v_mul_f32_e32 v1, 0xbfb8aa3b, v1
	v_pk_mul_f32 v[108:109], v[108:109], v[172:173]
	v_pk_add_f32 v[172:173], v[204:205], 1.0 op_sel_hi:[1,0]
	v_exp_f32_e32 v1, v1
	v_pk_mul_f32 v[172:173], v[202:203], v[172:173]
	v_pk_add_f32 v[174:175], v[178:179], 1.0 op_sel_hi:[1,0]
	v_pk_mul_f32 v[114:115], v[114:115], v[172:173]
	v_and_b32_e32 v172, 0xffff0000, v168
	v_lshlrev_b32_e32 v168, 16, v170
	v_pk_mul_f32 v[174:175], v[176:177], v[174:175]
	v_lshlrev_b32_e32 v176, 16, v165
	v_and_b32_e32 v178, 0xffff0000, v165
	v_lshlrev_b32_e32 v165, 16, v166
	v_and_b32_e32 v179, 0xffff0000, v166
	v_mul_f32_e32 v166, 0xbfb8aa3b, v168
	v_pk_mul_f32 v[112:113], v[112:113], v[174:175]
	v_lshlrev_b32_e32 v173, 16, v169
	v_and_b32_e32 v175, 0xffff0000, v169
	v_and_b32_e32 v169, 0xffff0000, v170
	v_lshlrev_b32_e32 v170, 16, v164
	v_lshlrev_b32_e32 v198, 16, v167
	v_and_b32_e32 v199, 0xffff0000, v167
	v_add_f32_e32 v1, 1.0, v1
	v_exp_f32_e32 v167, v166
	v_lshlrev_b32_e32 v174, 16, v171
	v_and_b32_e32 v177, 0xffff0000, v171
	v_and_b32_e32 v171, 0xffff0000, v164
	v_rcp_f32_e32 v164, v1
	v_max_f32_e64 v1, -v170, -v170
	v_min_f32_e32 v1, 0x42a00000, v1
	v_mul_f32_e32 v1, 0x3fb8aa3b, v1
	v_exp_f32_e32 v166, v1
	v_add_f32_e32 v1, 1.0, v167
	v_rcp_f32_e32 v168, v1
	v_max_f32_e64 v1, -v165, -v165
	v_mul_f32_e32 v165, 0xbfb8aa3b, v172
	v_exp_f32_e32 v165, v165
	v_min_f32_e32 v1, 0x42a00000, v1
	v_mul_f32_e32 v1, 0x3fb8aa3b, v1
	v_mul_f32_e32 v167, 0xbfb8aa3b, v169
	v_exp_f32_e32 v170, v1
	v_add_f32_e32 v1, 1.0, v165
	v_exp_f32_e32 v169, v167
	v_rcp_f32_e32 v165, v1
	v_max_f32_e64 v1, -v171, -v171
	v_min_f32_e32 v1, 0x42a00000, v1
	v_mul_f32_e32 v1, 0x3fb8aa3b, v1
	v_mul_f32_e32 v171, 0xbfb8aa3b, v173
	v_exp_f32_e32 v167, v1
	v_add_f32_e32 v1, 1.0, v169
	v_exp_f32_e32 v172, v171
	v_rcp_f32_e32 v169, v1
	v_max_f32_e64 v1, -v179, -v179
	v_min_f32_e32 v1, 0x42a00000, v1
	v_mul_f32_e32 v1, 0x3fb8aa3b, v1
	v_mul_f32_e32 v173, 0xbfb8aa3b, v174
	v_exp_f32_e32 v171, v1
	v_add_f32_e32 v1, 1.0, v172
	v_exp_f32_e32 v173, v173
	v_rcp_f32_e32 v172, v1
	v_max_f32_e64 v1, -v176, -v176
	v_min_f32_e32 v1, 0x42a00000, v1
	v_mul_f32_e32 v1, 0x3fb8aa3b, v1
	v_exp_f32_e32 v174, v1
	v_add_f32_e32 v1, 1.0, v173
	v_mul_f32_e32 v173, 0xbfb8aa3b, v175
	v_exp_f32_e32 v173, v173
	v_rcp_f32_e32 v176, v1
	v_max_f32_e64 v1, -v198, -v198
	v_max_f32_e64 v175, -v178, -v178
	v_min_f32_e32 v1, 0x42a00000, v1
	v_min_f32_e32 v175, 0x42a00000, v175
	v_mul_f32_e32 v1, 0x3fb8aa3b, v1
	v_mul_f32_e32 v175, 0x3fb8aa3b, v175
	v_exp_f32_e32 v175, v175
	v_exp_f32_e32 v178, v1
	v_add_f32_e32 v1, 1.0, v173
	v_rcp_f32_e32 v173, v1
	v_pk_add_f32 v[174:175], v[174:175], 1.0 op_sel_hi:[1,0]
	v_pk_add_f32 v[166:167], v[166:167], 1.0 op_sel_hi:[1,0]
	v_mul_f32_e32 v1, 0xbfb8aa3b, v177
	v_pk_mul_f32 v[164:165], v[164:165], v[166:167]
	v_pk_mul_f32 v[166:167], v[172:173], v[174:175]
	v_exp_f32_e32 v1, v1
	v_pk_mul_f32 v[102:103], v[102:103], v[166:167]
	v_max_f32_e64 v166, -v199, -v199
	v_min_f32_e32 v166, 0x42a00000, v166
	v_mul_f32_e32 v166, 0x3fb8aa3b, v166
	v_exp_f32_e32 v179, v166
	v_add_f32_e32 v1, 1.0, v1
	v_rcp_f32_e32 v177, v1
	v_lshlrev_b32_e32 v1, 16, v160
	v_mul_f32_e32 v1, 0xbfb8aa3b, v1
	v_pk_mul_f32 v[100:101], v[100:101], v[164:165]
	v_pk_add_f32 v[164:165], v[178:179], 1.0 op_sel_hi:[1,0]
	v_exp_f32_e32 v1, v1
	v_pk_mul_f32 v[164:165], v[176:177], v[164:165]
	v_pk_add_f32 v[166:167], v[170:171], 1.0 op_sel_hi:[1,0]
	v_pk_mul_f32 v[106:107], v[106:107], v[164:165]
	v_and_b32_e32 v164, 0xffff0000, v160
	v_lshlrev_b32_e32 v160, 16, v162
	v_pk_mul_f32 v[166:167], v[168:169], v[166:167]
	v_lshlrev_b32_e32 v168, 16, v157
	v_and_b32_e32 v170, 0xffff0000, v157
	v_lshlrev_b32_e32 v157, 16, v158
	v_and_b32_e32 v171, 0xffff0000, v158
	v_mul_f32_e32 v158, 0xbfb8aa3b, v160
	v_pk_mul_f32 v[104:105], v[104:105], v[166:167]
	v_lshlrev_b32_e32 v165, 16, v161
	v_and_b32_e32 v167, 0xffff0000, v161
	v_and_b32_e32 v161, 0xffff0000, v162
	v_lshlrev_b32_e32 v162, 16, v156
	v_lshlrev_b32_e32 v172, 16, v159
	v_and_b32_e32 v173, 0xffff0000, v159
	v_add_f32_e32 v1, 1.0, v1
	v_exp_f32_e32 v159, v158
	v_lshlrev_b32_e32 v166, 16, v163
	v_and_b32_e32 v169, 0xffff0000, v163
	v_and_b32_e32 v163, 0xffff0000, v156
	v_rcp_f32_e32 v156, v1
	v_max_f32_e64 v1, -v162, -v162
	v_min_f32_e32 v1, 0x42a00000, v1
	v_mul_f32_e32 v1, 0x3fb8aa3b, v1
	v_exp_f32_e32 v158, v1
	v_add_f32_e32 v1, 1.0, v159
	v_rcp_f32_e32 v160, v1
	v_max_f32_e64 v1, -v157, -v157
	v_mul_f32_e32 v157, 0xbfb8aa3b, v164
	v_exp_f32_e32 v157, v157
	v_min_f32_e32 v1, 0x42a00000, v1
	v_mul_f32_e32 v1, 0x3fb8aa3b, v1
	v_mul_f32_e32 v159, 0xbfb8aa3b, v161
	v_exp_f32_e32 v162, v1
	v_add_f32_e32 v1, 1.0, v157
	v_exp_f32_e32 v161, v159
	v_rcp_f32_e32 v157, v1
	v_max_f32_e64 v1, -v163, -v163
	v_min_f32_e32 v1, 0x42a00000, v1
	v_mul_f32_e32 v1, 0x3fb8aa3b, v1
	v_mul_f32_e32 v163, 0xbfb8aa3b, v165
	v_exp_f32_e32 v159, v1
	v_add_f32_e32 v1, 1.0, v161
	v_exp_f32_e32 v164, v163
	v_rcp_f32_e32 v161, v1
	v_max_f32_e64 v1, -v171, -v171
	v_min_f32_e32 v1, 0x42a00000, v1
	v_mul_f32_e32 v1, 0x3fb8aa3b, v1
	v_mul_f32_e32 v165, 0xbfb8aa3b, v166
	v_exp_f32_e32 v163, v1
	v_add_f32_e32 v1, 1.0, v164
	v_exp_f32_e32 v165, v165
	v_rcp_f32_e32 v164, v1
	v_max_f32_e64 v1, -v168, -v168
	v_min_f32_e32 v1, 0x42a00000, v1
	v_mul_f32_e32 v1, 0x3fb8aa3b, v1
	v_exp_f32_e32 v166, v1
	v_add_f32_e32 v1, 1.0, v165
	v_mul_f32_e32 v165, 0xbfb8aa3b, v167
	v_exp_f32_e32 v165, v165
	v_rcp_f32_e32 v168, v1
	v_max_f32_e64 v1, -v172, -v172
	v_max_f32_e64 v167, -v170, -v170
	v_min_f32_e32 v1, 0x42a00000, v1
	v_min_f32_e32 v167, 0x42a00000, v167
	v_mul_f32_e32 v1, 0x3fb8aa3b, v1
	v_mul_f32_e32 v167, 0x3fb8aa3b, v167
	v_exp_f32_e32 v167, v167
	v_exp_f32_e32 v170, v1
	v_add_f32_e32 v1, 1.0, v165
	v_rcp_f32_e32 v165, v1
	v_pk_add_f32 v[166:167], v[166:167], 1.0 op_sel_hi:[1,0]
	v_pk_add_f32 v[158:159], v[158:159], 1.0 op_sel_hi:[1,0]
	v_mul_f32_e32 v1, 0xbfb8aa3b, v169
	v_pk_mul_f32 v[156:157], v[156:157], v[158:159]
	v_pk_mul_f32 v[158:159], v[164:165], v[166:167]
	v_exp_f32_e32 v1, v1
	v_pk_mul_f32 v[94:95], v[94:95], v[158:159]
	v_max_f32_e64 v158, -v173, -v173
	v_min_f32_e32 v158, 0x42a00000, v158
	v_mul_f32_e32 v158, 0x3fb8aa3b, v158
	v_exp_f32_e32 v171, v158
	v_add_f32_e32 v1, 1.0, v1
	v_rcp_f32_e32 v169, v1
	v_lshlrev_b32_e32 v1, 16, v152
	v_mul_f32_e32 v1, 0xbfb8aa3b, v1
	v_pk_mul_f32 v[92:93], v[92:93], v[156:157]
	v_pk_add_f32 v[156:157], v[170:171], 1.0 op_sel_hi:[1,0]
	v_exp_f32_e32 v1, v1
	v_pk_mul_f32 v[156:157], v[168:169], v[156:157]
	v_pk_add_f32 v[158:159], v[162:163], 1.0 op_sel_hi:[1,0]
	v_pk_mul_f32 v[98:99], v[98:99], v[156:157]
	v_and_b32_e32 v156, 0xffff0000, v152
	v_lshlrev_b32_e32 v152, 16, v154
	v_pk_mul_f32 v[158:159], v[160:161], v[158:159]
	v_lshlrev_b32_e32 v160, 16, v149
	v_and_b32_e32 v162, 0xffff0000, v149
	v_lshlrev_b32_e32 v149, 16, v150
	v_and_b32_e32 v163, 0xffff0000, v150
	v_mul_f32_e32 v150, 0xbfb8aa3b, v152
	v_pk_mul_f32 v[96:97], v[96:97], v[158:159]
	v_lshlrev_b32_e32 v157, 16, v153
	v_and_b32_e32 v159, 0xffff0000, v153
	v_and_b32_e32 v153, 0xffff0000, v154
	v_lshlrev_b32_e32 v154, 16, v148
	v_lshlrev_b32_e32 v164, 16, v151
	v_and_b32_e32 v165, 0xffff0000, v151
	v_add_f32_e32 v1, 1.0, v1
	v_exp_f32_e32 v151, v150
	v_lshlrev_b32_e32 v158, 16, v155
	v_and_b32_e32 v161, 0xffff0000, v155
	v_and_b32_e32 v155, 0xffff0000, v148
	v_rcp_f32_e32 v148, v1
	v_max_f32_e64 v1, -v154, -v154
	v_min_f32_e32 v1, 0x42a00000, v1
	v_mul_f32_e32 v1, 0x3fb8aa3b, v1
	v_exp_f32_e32 v150, v1
	v_add_f32_e32 v1, 1.0, v151
	v_rcp_f32_e32 v152, v1
	v_max_f32_e64 v1, -v149, -v149
	v_mul_f32_e32 v149, 0xbfb8aa3b, v156
	v_exp_f32_e32 v149, v149
	v_min_f32_e32 v1, 0x42a00000, v1
	v_mul_f32_e32 v1, 0x3fb8aa3b, v1
	v_mul_f32_e32 v151, 0xbfb8aa3b, v153
	v_exp_f32_e32 v154, v1
	v_add_f32_e32 v1, 1.0, v149
	v_exp_f32_e32 v153, v151
	v_rcp_f32_e32 v149, v1
	v_max_f32_e64 v1, -v155, -v155
	v_min_f32_e32 v1, 0x42a00000, v1
	v_mul_f32_e32 v1, 0x3fb8aa3b, v1
	v_mul_f32_e32 v155, 0xbfb8aa3b, v157
	v_exp_f32_e32 v151, v1
	v_add_f32_e32 v1, 1.0, v153
	v_exp_f32_e32 v156, v155
	v_rcp_f32_e32 v153, v1
	v_max_f32_e64 v1, -v163, -v163
	v_min_f32_e32 v1, 0x42a00000, v1
	v_mul_f32_e32 v1, 0x3fb8aa3b, v1
	v_mul_f32_e32 v157, 0xbfb8aa3b, v158
	v_exp_f32_e32 v155, v1
	v_add_f32_e32 v1, 1.0, v156
	v_exp_f32_e32 v157, v157
	v_rcp_f32_e32 v156, v1
	v_max_f32_e64 v1, -v160, -v160
	v_min_f32_e32 v1, 0x42a00000, v1
	v_mul_f32_e32 v1, 0x3fb8aa3b, v1
	v_exp_f32_e32 v158, v1
	v_add_f32_e32 v1, 1.0, v157
	v_mul_f32_e32 v157, 0xbfb8aa3b, v159
	v_exp_f32_e32 v157, v157
	v_rcp_f32_e32 v160, v1
	v_max_f32_e64 v1, -v164, -v164
	v_max_f32_e64 v159, -v162, -v162
	v_min_f32_e32 v1, 0x42a00000, v1
	v_min_f32_e32 v159, 0x42a00000, v159
	v_mul_f32_e32 v1, 0x3fb8aa3b, v1
	v_mul_f32_e32 v159, 0x3fb8aa3b, v159
	v_exp_f32_e32 v159, v159
	v_exp_f32_e32 v162, v1
	v_add_f32_e32 v1, 1.0, v157
	v_rcp_f32_e32 v157, v1
	v_pk_add_f32 v[158:159], v[158:159], 1.0 op_sel_hi:[1,0]
	v_pk_add_f32 v[150:151], v[150:151], 1.0 op_sel_hi:[1,0]
	v_mul_f32_e32 v1, 0xbfb8aa3b, v161
	v_pk_mul_f32 v[148:149], v[148:149], v[150:151]
	v_pk_mul_f32 v[150:151], v[156:157], v[158:159]
	v_exp_f32_e32 v1, v1
	v_pk_mul_f32 v[86:87], v[86:87], v[150:151]
	v_max_f32_e64 v150, -v165, -v165
	v_min_f32_e32 v150, 0x42a00000, v150
	v_mul_f32_e32 v150, 0x3fb8aa3b, v150
	v_exp_f32_e32 v163, v150
	v_add_f32_e32 v1, 1.0, v1
	v_rcp_f32_e32 v161, v1
	v_lshlrev_b32_e32 v1, 16, v144
	v_mul_f32_e32 v1, 0xbfb8aa3b, v1
	v_pk_mul_f32 v[84:85], v[84:85], v[148:149]
	v_pk_add_f32 v[148:149], v[162:163], 1.0 op_sel_hi:[1,0]
	v_exp_f32_e32 v1, v1
	v_pk_mul_f32 v[148:149], v[160:161], v[148:149]
	v_pk_add_f32 v[150:151], v[154:155], 1.0 op_sel_hi:[1,0]
	v_pk_mul_f32 v[90:91], v[90:91], v[148:149]
	v_and_b32_e32 v148, 0xffff0000, v144
	v_lshlrev_b32_e32 v144, 16, v146
	v_pk_mul_f32 v[150:151], v[152:153], v[150:151]
	v_lshlrev_b32_e32 v152, 16, v141
	v_and_b32_e32 v154, 0xffff0000, v141
	v_lshlrev_b32_e32 v141, 16, v142
	v_and_b32_e32 v155, 0xffff0000, v142
	v_mul_f32_e32 v142, 0xbfb8aa3b, v144
	v_pk_mul_f32 v[88:89], v[88:89], v[150:151]
	v_lshlrev_b32_e32 v149, 16, v145
	v_and_b32_e32 v151, 0xffff0000, v145
	v_and_b32_e32 v145, 0xffff0000, v146
	v_lshlrev_b32_e32 v146, 16, v140
	v_lshlrev_b32_e32 v156, 16, v143
	v_and_b32_e32 v157, 0xffff0000, v143
	v_add_f32_e32 v1, 1.0, v1
	v_exp_f32_e32 v143, v142
	v_lshlrev_b32_e32 v150, 16, v147
	v_and_b32_e32 v153, 0xffff0000, v147
	v_and_b32_e32 v147, 0xffff0000, v140
	v_rcp_f32_e32 v140, v1
	v_max_f32_e64 v1, -v146, -v146
	v_min_f32_e32 v1, 0x42a00000, v1
	v_mul_f32_e32 v1, 0x3fb8aa3b, v1
	v_exp_f32_e32 v142, v1
	v_add_f32_e32 v1, 1.0, v143
	v_rcp_f32_e32 v144, v1
	v_max_f32_e64 v1, -v141, -v141
	v_mul_f32_e32 v141, 0xbfb8aa3b, v148
	v_exp_f32_e32 v141, v141
	v_min_f32_e32 v1, 0x42a00000, v1
	v_mul_f32_e32 v1, 0x3fb8aa3b, v1
	v_mul_f32_e32 v143, 0xbfb8aa3b, v145
	v_exp_f32_e32 v146, v1
	v_add_f32_e32 v1, 1.0, v141
	v_exp_f32_e32 v145, v143
	v_rcp_f32_e32 v141, v1
	v_max_f32_e64 v1, -v147, -v147
	v_min_f32_e32 v1, 0x42a00000, v1
	v_mul_f32_e32 v1, 0x3fb8aa3b, v1
	v_mul_f32_e32 v147, 0xbfb8aa3b, v149
	v_exp_f32_e32 v143, v1
	v_add_f32_e32 v1, 1.0, v145
	v_exp_f32_e32 v148, v147
	v_rcp_f32_e32 v145, v1
	v_max_f32_e64 v1, -v155, -v155
	v_min_f32_e32 v1, 0x42a00000, v1
	v_mul_f32_e32 v1, 0x3fb8aa3b, v1
	v_mul_f32_e32 v149, 0xbfb8aa3b, v150
	v_exp_f32_e32 v147, v1
	v_add_f32_e32 v1, 1.0, v148
	v_exp_f32_e32 v149, v149
	v_rcp_f32_e32 v148, v1
	v_max_f32_e64 v1, -v152, -v152
	v_min_f32_e32 v1, 0x42a00000, v1
	v_mul_f32_e32 v1, 0x3fb8aa3b, v1
	v_exp_f32_e32 v150, v1
	v_add_f32_e32 v1, 1.0, v149
	v_mul_f32_e32 v149, 0xbfb8aa3b, v151
	v_exp_f32_e32 v149, v149
	v_rcp_f32_e32 v152, v1
	v_max_f32_e64 v1, -v156, -v156
	v_max_f32_e64 v151, -v154, -v154
	v_min_f32_e32 v1, 0x42a00000, v1
	v_min_f32_e32 v151, 0x42a00000, v151
	v_mul_f32_e32 v1, 0x3fb8aa3b, v1
	v_mul_f32_e32 v151, 0x3fb8aa3b, v151
	v_exp_f32_e32 v151, v151
	v_exp_f32_e32 v154, v1
	v_add_f32_e32 v1, 1.0, v149
	v_rcp_f32_e32 v149, v1
	v_pk_add_f32 v[150:151], v[150:151], 1.0 op_sel_hi:[1,0]
	v_pk_add_f32 v[142:143], v[142:143], 1.0 op_sel_hi:[1,0]
	v_mul_f32_e32 v1, 0xbfb8aa3b, v153
	v_pk_mul_f32 v[140:141], v[140:141], v[142:143]
	v_pk_mul_f32 v[142:143], v[148:149], v[150:151]
	v_exp_f32_e32 v1, v1
	v_pk_mul_f32 v[78:79], v[78:79], v[142:143]
	v_max_f32_e64 v142, -v157, -v157
	v_min_f32_e32 v142, 0x42a00000, v142
	v_mul_f32_e32 v142, 0x3fb8aa3b, v142
	v_exp_f32_e32 v155, v142
	v_add_f32_e32 v1, 1.0, v1
	v_rcp_f32_e32 v153, v1
	v_lshlrev_b32_e32 v1, 16, v136
	v_mul_f32_e32 v1, 0xbfb8aa3b, v1
	v_pk_mul_f32 v[76:77], v[76:77], v[140:141]
	v_pk_add_f32 v[140:141], v[154:155], 1.0 op_sel_hi:[1,0]
	v_exp_f32_e32 v1, v1
	v_pk_mul_f32 v[140:141], v[152:153], v[140:141]
	v_pk_add_f32 v[142:143], v[146:147], 1.0 op_sel_hi:[1,0]
	v_pk_mul_f32 v[82:83], v[82:83], v[140:141]
	v_and_b32_e32 v140, 0xffff0000, v136
	v_lshlrev_b32_e32 v136, 16, v138
	v_pk_mul_f32 v[142:143], v[144:145], v[142:143]
	v_lshlrev_b32_e32 v145, 16, v133
	v_and_b32_e32 v148, 0xffff0000, v133
	v_lshlrev_b32_e32 v133, 16, v134
	v_and_b32_e32 v141, 0xffff0000, v134
	v_mul_f32_e32 v134, 0xbfb8aa3b, v136
	v_pk_mul_f32 v[80:81], v[80:81], v[142:143]
	v_lshlrev_b32_e32 v142, 16, v137
	v_and_b32_e32 v143, 0xffff0000, v137
	v_and_b32_e32 v137, 0xffff0000, v138
	v_lshlrev_b32_e32 v138, 16, v132
	v_lshlrev_b32_e32 v149, 16, v135
	v_and_b32_e32 v150, 0xffff0000, v135
	v_add_f32_e32 v1, 1.0, v1
	v_exp_f32_e32 v135, v134
	v_lshlrev_b32_e32 v144, 16, v139
	v_and_b32_e32 v147, 0xffff0000, v139
	v_and_b32_e32 v139, 0xffff0000, v132
	v_rcp_f32_e32 v132, v1
	v_max_f32_e64 v1, -v138, -v138
	v_min_f32_e32 v1, 0x42a00000, v1
	v_mul_f32_e32 v1, 0x3fb8aa3b, v1
	v_exp_f32_e32 v134, v1
	v_add_f32_e32 v1, 1.0, v135
	v_rcp_f32_e32 v136, v1
	v_max_f32_e64 v1, -v133, -v133
	v_mul_f32_e32 v133, 0xbfb8aa3b, v140
	v_exp_f32_e32 v133, v133
	v_min_f32_e32 v1, 0x42a00000, v1
	v_mul_f32_e32 v1, 0x3fb8aa3b, v1
	v_mul_f32_e32 v135, 0xbfb8aa3b, v137
	v_exp_f32_e32 v138, v1
	v_add_f32_e32 v1, 1.0, v133
	v_exp_f32_e32 v137, v135
	v_rcp_f32_e32 v133, v1
	v_max_f32_e64 v1, -v139, -v139
	v_min_f32_e32 v1, 0x42a00000, v1
	v_mul_f32_e32 v1, 0x3fb8aa3b, v1
	v_exp_f32_e32 v135, v1
	v_add_f32_e32 v1, 1.0, v137
	v_add_co_u32_e32 v140, vcc, s86, v2
	v_rcp_f32_e32 v137, v1
	v_max_f32_e64 v1, -v141, -v141
	v_addc_co_u32_e32 v141, vcc, 0, v3, vcc
	global_load_dwordx4 v[198:201], v[140:141], off
	v_mul_f32_e32 v139, 0xbfb8aa3b, v142
	v_exp_f32_e32 v140, v139
	v_min_f32_e32 v1, 0x42a00000, v1
	v_mul_f32_e32 v1, 0x3fb8aa3b, v1
	v_exp_f32_e32 v139, v1
	v_add_f32_e32 v1, 1.0, v140
	v_lshl_add_u64 v[140:141], v[2:3], 0, s[42:43]
	global_load_dwordx4 v[202:205], v[140:141], off offset:2048
	global_load_dwordx4 v[206:209], v[140:141], off offset:256
	global_load_dwordx4 v[210:213], v[140:141], off offset:2304
	v_mul_f32_e32 v144, 0xbfb8aa3b, v144
	v_rcp_f32_e32 v142, v1
	v_max_f32_e64 v1, -v145, -v145
	v_exp_f32_e32 v145, v144
	v_min_f32_e32 v1, 0x42a00000, v1
	v_mul_f32_e32 v1, 0x3fb8aa3b, v1
	v_mul_f32_e32 v143, 0xbfb8aa3b, v143
	v_exp_f32_e32 v144, v1
	v_add_f32_e32 v1, 1.0, v145
	v_exp_f32_e32 v143, v143
	v_rcp_f32_e32 v146, v1
	v_max_f32_e64 v1, -v149, -v149
	v_max_f32_e64 v145, -v148, -v148
	v_min_f32_e32 v1, 0x42a00000, v1
	v_min_f32_e32 v145, 0x42a00000, v145
	v_mul_f32_e32 v1, 0x3fb8aa3b, v1
	v_mul_f32_e32 v145, 0x3fb8aa3b, v145
	v_exp_f32_e32 v145, v145
	v_exp_f32_e32 v148, v1
	v_add_f32_e32 v1, 1.0, v143
	v_rcp_f32_e32 v143, v1
	v_pk_add_f32 v[144:145], v[144:145], 1.0 op_sel_hi:[1,0]
	v_pk_add_f32 v[134:135], v[134:135], 1.0 op_sel_hi:[1,0]
	v_mul_f32_e32 v1, 0xbfb8aa3b, v147
	v_pk_mul_f32 v[132:133], v[132:133], v[134:135]
	v_pk_mul_f32 v[134:135], v[142:143], v[144:145]
	v_exp_f32_e32 v1, v1
	v_pk_mul_f32 v[70:71], v[70:71], v[134:135]
	v_max_f32_e64 v134, -v150, -v150
	v_min_f32_e32 v134, 0x42a00000, v134
	v_mul_f32_e32 v134, 0x3fb8aa3b, v134
	v_exp_f32_e32 v149, v134
	v_add_f32_e32 v1, 1.0, v1
	v_rcp_f32_e32 v147, v1
	v_pk_add_f32 v[134:135], v[138:139], 1.0 op_sel_hi:[1,0]
	v_pk_mul_f32 v[68:69], v[68:69], v[132:133]
	v_pk_add_f32 v[132:133], v[148:149], 1.0 op_sel_hi:[1,0]
	v_pk_mul_f32 v[134:135], v[136:137], v[134:135]
	v_pk_mul_f32 v[132:133], v[146:147], v[132:133]
	v_pk_mul_f32 v[72:73], v[72:73], v[134:135]
	v_add_co_u32_e32 v134, vcc, s87, v2
	v_pk_mul_f32 v[74:75], v[74:75], v[132:133]
	v_lshl_add_u64 v[132:133], v[2:3], 0, s[44:45]
	v_addc_co_u32_e32 v135, vcc, 0, v3, vcc
	global_load_dwordx4 v[172:175], v[132:133], off offset:2048
	global_load_dwordx4 v[168:171], v[132:133], off offset:256
	global_load_dwordx4 v[176:179], v[134:135], off
	global_load_dwordx4 v[164:167], v[132:133], off offset:2304
	v_add_co_u32_e32 v134, vcc, s88, v2
	v_lshl_add_u64 v[132:133], v[2:3], 0, s[46:47]
	s_nop 0
	v_addc_co_u32_e32 v135, vcc, 0, v3, vcc
	global_load_dwordx4 v[156:159], v[132:133], off offset:2048
	global_load_dwordx4 v[152:155], v[132:133], off offset:256
	global_load_dwordx4 v[160:163], v[134:135], off
	global_load_dwordx4 v[148:151], v[132:133], off offset:2304
	v_lshl_add_u64 v[132:133], v[2:3], 0, s[48:49]
	v_add_co_u32_e32 v2, vcc, s89, v2
	s_waitcnt vmcnt(8)
	v_lshlrev_b32_e32 v1, 16, v198
	v_mul_f32_e32 v1, 0xbfb8aa3b, v1
	v_exp_f32_e32 v1, v1
	v_addc_co_u32_e32 v3, vcc, 0, v3, vcc
	global_load_dwordx4 v[140:143], v[132:133], off offset:2048
	global_load_dwordx4 v[136:139], v[132:133], off offset:256
	global_load_dwordx4 v[144:147], v[2:3], off
	s_nop 0
	global_load_dwordx4 v[132:135], v[132:133], off offset:2304
	v_and_b32_e32 v3, 0xffff0000, v198
	v_lshlrev_b32_e32 v198, 16, v200
	v_lshlrev_b32_e32 v214, 16, v199
	v_and_b32_e32 v215, 0xffff0000, v199
	v_and_b32_e32 v199, 0xffff0000, v200
	v_lshlrev_b32_e32 v200, 16, v202
	v_add_f32_e32 v1, 1.0, v1
	v_mul_f32_e32 v198, 0xbfb8aa3b, v198
	v_rcp_f32_e32 v2, v1
	v_max_f32_e64 v1, -v200, -v200
	v_exp_f32_e32 v200, v198
	v_min_f32_e32 v1, 0x42a00000, v1
	v_mul_f32_e32 v1, 0x3fb8aa3b, v1
	v_mul_f32_e32 v3, 0xbfb8aa3b, v3
	v_lshlrev_b32_e32 v216, 16, v201
	v_and_b32_e32 v217, 0xffff0000, v201
	v_and_b32_e32 v201, 0xffff0000, v202
	v_lshlrev_b32_e32 v202, 16, v204
	v_exp_f32_e32 v198, v1
	v_add_f32_e32 v1, 1.0, v200
	v_exp_f32_e32 v3, v3
	v_rcp_f32_e32 v200, v1
	v_max_f32_e64 v1, -v202, -v202
	v_min_f32_e32 v1, 0x42a00000, v1
	v_mul_f32_e32 v1, 0x3fb8aa3b, v1
	v_exp_f32_e32 v202, v1
	v_add_f32_e32 v1, 1.0, v3
	v_mul_f32_e32 v199, 0xbfb8aa3b, v199
	v_rcp_f32_e32 v3, v1
	v_max_f32_e64 v1, -v201, -v201
	v_exp_f32_e32 v201, v199
	v_min_f32_e32 v1, 0x42a00000, v1
	v_mul_f32_e32 v1, 0x3fb8aa3b, v1
	v_lshlrev_b32_e32 v218, 16, v203
	v_and_b32_e32 v219, 0xffff0000, v203
	v_and_b32_e32 v203, 0xffff0000, v204
	v_exp_f32_e32 v199, v1
	v_add_f32_e32 v1, 1.0, v201
	v_rcp_f32_e32 v201, v1
	v_max_f32_e64 v1, -v203, -v203
	v_mul_f32_e32 v203, 0xbfb8aa3b, v214
	v_exp_f32_e32 v204, v203
	v_min_f32_e32 v1, 0x42a00000, v1
	v_lshlrev_b32_e32 v220, 16, v205
	v_and_b32_e32 v221, 0xffff0000, v205
	v_mul_f32_e32 v1, 0x3fb8aa3b, v1
	v_mul_f32_e32 v205, 0xbfb8aa3b, v216
	v_exp_f32_e32 v203, v1
	v_add_f32_e32 v1, 1.0, v204
	v_exp_f32_e32 v205, v205
	v_rcp_f32_e32 v204, v1
	v_max_f32_e64 v1, -v218, -v218
	v_min_f32_e32 v1, 0x42a00000, v1
	v_mul_f32_e32 v1, 0x3fb8aa3b, v1
	v_exp_f32_e32 v214, v1
	v_add_f32_e32 v1, 1.0, v205
	v_mul_f32_e32 v205, 0xbfb8aa3b, v215
	v_exp_f32_e32 v205, v205
	v_rcp_f32_e32 v216, v1
	v_max_f32_e64 v1, -v220, -v220
	v_max_f32_e64 v215, -v219, -v219
	v_min_f32_e32 v1, 0x42a00000, v1
	v_min_f32_e32 v215, 0x42a00000, v215
	v_mul_f32_e32 v1, 0x3fb8aa3b, v1
	v_mul_f32_e32 v215, 0x3fb8aa3b, v215
	v_exp_f32_e32 v215, v215
	v_exp_f32_e32 v218, v1
	v_add_f32_e32 v1, 1.0, v205
	v_rcp_f32_e32 v205, v1
	v_mul_f32_e32 v1, 0xbfb8aa3b, v217
	v_exp_f32_e32 v1, v1
	v_pk_add_f32 v[214:215], v[214:215], 1.0 op_sel_hi:[1,0]
	v_pk_add_f32 v[198:199], v[198:199], 1.0 op_sel_hi:[1,0]
	v_add_f32_e32 v1, 1.0, v1
	v_pk_mul_f32 v[2:3], v[2:3], v[198:199]
	v_pk_mul_f32 v[198:199], v[204:205], v[214:215]
	v_rcp_f32_e32 v217, v1
	v_pk_mul_f32 v[62:63], v[62:63], v[198:199]
	v_max_f32_e64 v198, -v221, -v221
	v_min_f32_e32 v198, 0x42a00000, v198
	v_mul_f32_e32 v198, 0x3fb8aa3b, v198
	v_lshlrev_b32_e32 v1, 16, v206
	v_exp_f32_e32 v219, v198
	v_mul_f32_e32 v1, 0xbfb8aa3b, v1
	v_exp_f32_e32 v1, v1
	v_pk_add_f32 v[198:199], v[202:203], 1.0 op_sel_hi:[1,0]
	v_pk_mul_f32 v[60:61], v[60:61], v[2:3]
	v_pk_mul_f32 v[198:199], v[200:201], v[198:199]
	v_pk_add_f32 v[2:3], v[218:219], 1.0 op_sel_hi:[1,0]
	v_pk_mul_f32 v[64:65], v[64:65], v[198:199]
	v_lshlrev_b32_e32 v198, 16, v208
	v_pk_mul_f32 v[2:3], v[216:217], v[2:3]
	v_lshlrev_b32_e32 v200, 16, v210
	v_add_f32_e32 v1, 1.0, v1
	v_mul_f32_e32 v198, 0xbfb8aa3b, v198
	v_pk_mul_f32 v[66:67], v[66:67], v[2:3]
	v_rcp_f32_e32 v2, v1
	v_max_f32_e64 v1, -v200, -v200
	v_exp_f32_e32 v200, v198
	v_and_b32_e32 v3, 0xffff0000, v206
	v_min_f32_e32 v1, 0x42a00000, v1
	v_mul_f32_e32 v1, 0x3fb8aa3b, v1
	v_mul_f32_e32 v3, 0xbfb8aa3b, v3
	v_lshlrev_b32_e32 v202, 16, v212
	v_exp_f32_e32 v198, v1
	v_add_f32_e32 v1, 1.0, v200
	v_exp_f32_e32 v3, v3
	v_rcp_f32_e32 v200, v1
	v_max_f32_e64 v1, -v202, -v202
	v_min_f32_e32 v1, 0x42a00000, v1
	v_and_b32_e32 v199, 0xffff0000, v208
	v_mul_f32_e32 v1, 0x3fb8aa3b, v1
	v_and_b32_e32 v201, 0xffff0000, v210
	v_exp_f32_e32 v202, v1
	v_add_f32_e32 v1, 1.0, v3
	v_mul_f32_e32 v199, 0xbfb8aa3b, v199
	v_rcp_f32_e32 v3, v1
	v_max_f32_e64 v1, -v201, -v201
	v_exp_f32_e32 v201, v199
	v_min_f32_e32 v1, 0x42a00000, v1
	v_lshlrev_b32_e32 v203, 16, v207
	v_mul_f32_e32 v1, 0x3fb8aa3b, v1
	v_and_b32_e32 v204, 0xffff0000, v212
	v_exp_f32_e32 v199, v1
	v_add_f32_e32 v1, 1.0, v201
	v_mul_f32_e32 v203, 0xbfb8aa3b, v203
	v_rcp_f32_e32 v201, v1
	v_max_f32_e64 v1, -v204, -v204
	v_exp_f32_e32 v204, v203
	v_min_f32_e32 v1, 0x42a00000, v1
	v_lshlrev_b32_e32 v206, 16, v209
	v_mul_f32_e32 v1, 0x3fb8aa3b, v1
	v_and_b32_e32 v205, 0xffff0000, v207
	v_lshlrev_b32_e32 v207, 16, v211
	v_exp_f32_e32 v203, v1
	v_add_f32_e32 v1, 1.0, v204
	v_mul_f32_e32 v206, 0xbfb8aa3b, v206
	v_rcp_f32_e32 v204, v1
	v_max_f32_e64 v1, -v207, -v207
	v_exp_f32_e32 v207, v206
	v_min_f32_e32 v1, 0x42a00000, v1
	v_mul_f32_e32 v1, 0x3fb8aa3b, v1
	v_mul_f32_e32 v205, 0xbfb8aa3b, v205
	v_and_b32_e32 v210, 0xffff0000, v211
	v_lshlrev_b32_e32 v211, 16, v213
	v_exp_f32_e32 v206, v1
	v_add_f32_e32 v1, 1.0, v207
	v_exp_f32_e32 v205, v205
	v_rcp_f32_e32 v208, v1
	v_max_f32_e64 v1, -v211, -v211
	v_max_f32_e64 v207, -v210, -v210
	v_min_f32_e32 v1, 0x42a00000, v1
	v_min_f32_e32 v207, 0x42a00000, v207
	v_mul_f32_e32 v1, 0x3fb8aa3b, v1
	v_mul_f32_e32 v207, 0x3fb8aa3b, v207
	v_exp_f32_e32 v207, v207
	v_exp_f32_e32 v210, v1
	v_add_f32_e32 v1, 1.0, v205
	v_rcp_f32_e32 v205, v1
	v_and_b32_e32 v209, 0xffff0000, v209
	v_pk_add_f32 v[206:207], v[206:207], 1.0 op_sel_hi:[1,0]
	v_pk_add_f32 v[198:199], v[198:199], 1.0 op_sel_hi:[1,0]
	v_mul_f32_e32 v1, 0xbfb8aa3b, v209
	v_and_b32_e32 v212, 0xffff0000, v213
	v_pk_mul_f32 v[2:3], v[2:3], v[198:199]
	v_pk_mul_f32 v[198:199], v[204:205], v[206:207]
	v_exp_f32_e32 v1, v1
	v_pk_mul_f32 v[54:55], v[54:55], v[198:199]
	v_max_f32_e64 v198, -v212, -v212
	v_min_f32_e32 v198, 0x42a00000, v198
	v_mul_f32_e32 v198, 0x3fb8aa3b, v198
	v_exp_f32_e32 v211, v198
	v_add_f32_e32 v1, 1.0, v1
	v_rcp_f32_e32 v209, v1
	s_waitcnt vmcnt(4)
	v_lshlrev_b32_e32 v1, 16, v176
	v_mul_f32_e32 v1, 0xbfb8aa3b, v1
	v_pk_mul_f32 v[52:53], v[52:53], v[2:3]
	v_pk_add_f32 v[2:3], v[210:211], 1.0 op_sel_hi:[1,0]
	v_exp_f32_e32 v1, v1
	v_pk_add_f32 v[198:199], v[202:203], 1.0 op_sel_hi:[1,0]
	v_pk_mul_f32 v[2:3], v[208:209], v[2:3]
	v_pk_mul_f32 v[198:199], v[200:201], v[198:199]
	v_pk_mul_f32 v[58:59], v[58:59], v[2:3]
	v_and_b32_e32 v3, 0xffff0000, v176
	v_lshlrev_b32_e32 v176, 16, v178
	v_pk_mul_f32 v[56:57], v[56:57], v[198:199]
	v_lshlrev_b32_e32 v198, 16, v177
	v_and_b32_e32 v199, 0xffff0000, v177
	v_and_b32_e32 v177, 0xffff0000, v178
	v_lshlrev_b32_e32 v200, 16, v179
	v_and_b32_e32 v201, 0xffff0000, v179
	v_lshlrev_b32_e32 v178, 16, v172
	v_and_b32_e32 v179, 0xffff0000, v172
	v_mul_f32_e32 v172, 0xbfb8aa3b, v176
	v_lshlrev_b32_e32 v202, 16, v173
	v_and_b32_e32 v203, 0xffff0000, v173
	v_lshlrev_b32_e32 v173, 16, v174
	v_and_b32_e32 v204, 0xffff0000, v174
	v_add_f32_e32 v1, 1.0, v1
	v_exp_f32_e32 v174, v172
	v_rcp_f32_e32 v2, v1
	v_max_f32_e64 v1, -v178, -v178
	v_min_f32_e32 v1, 0x42a00000, v1
	v_mul_f32_e32 v1, 0x3fb8aa3b, v1
	v_mul_f32_e32 v3, 0xbfb8aa3b, v3
	v_exp_f32_e32 v172, v1
	v_add_f32_e32 v1, 1.0, v174
	v_exp_f32_e32 v3, v3
	v_rcp_f32_e32 v174, v1
	v_max_f32_e64 v1, -v173, -v173
	v_min_f32_e32 v1, 0x42a00000, v1
	v_mul_f32_e32 v1, 0x3fb8aa3b, v1
	v_mul_f32_e32 v173, 0xbfb8aa3b, v177
	v_lshlrev_b32_e32 v205, 16, v175
	v_and_b32_e32 v206, 0xffff0000, v175
	v_exp_f32_e32 v176, v1
	v_add_f32_e32 v1, 1.0, v3
	v_exp_f32_e32 v175, v173
	v_rcp_f32_e32 v3, v1
	v_max_f32_e64 v1, -v179, -v179
	v_min_f32_e32 v1, 0x42a00000, v1
	v_mul_f32_e32 v1, 0x3fb8aa3b, v1
	v_mul_f32_e32 v177, 0xbfb8aa3b, v198
	v_exp_f32_e32 v173, v1
	v_add_f32_e32 v1, 1.0, v175
	v_exp_f32_e32 v178, v177
	v_rcp_f32_e32 v175, v1
	v_max_f32_e64 v1, -v204, -v204
	v_min_f32_e32 v1, 0x42a00000, v1
	v_mul_f32_e32 v1, 0x3fb8aa3b, v1
	v_mul_f32_e32 v179, 0xbfb8aa3b, v200
	v_exp_f32_e32 v177, v1
	v_add_f32_e32 v1, 1.0, v178
	v_exp_f32_e32 v179, v179
	v_rcp_f32_e32 v178, v1
	v_max_f32_e64 v1, -v202, -v202
	v_min_f32_e32 v1, 0x42a00000, v1
	v_mul_f32_e32 v1, 0x3fb8aa3b, v1
	v_exp_f32_e32 v198, v1
	v_add_f32_e32 v1, 1.0, v179
	v_mul_f32_e32 v179, 0xbfb8aa3b, v199
	v_exp_f32_e32 v179, v179
	v_rcp_f32_e32 v200, v1
	v_max_f32_e64 v1, -v205, -v205
	v_max_f32_e64 v199, -v203, -v203
	v_min_f32_e32 v1, 0x42a00000, v1
	v_min_f32_e32 v199, 0x42a00000, v199
	v_mul_f32_e32 v1, 0x3fb8aa3b, v1
	v_mul_f32_e32 v199, 0x3fb8aa3b, v199
	v_exp_f32_e32 v199, v199
	v_exp_f32_e32 v202, v1
	v_add_f32_e32 v1, 1.0, v179
	v_rcp_f32_e32 v179, v1
	v_pk_add_f32 v[198:199], v[198:199], 1.0 op_sel_hi:[1,0]
	v_pk_add_f32 v[172:173], v[172:173], 1.0 op_sel_hi:[1,0]
	v_mul_f32_e32 v1, 0xbfb8aa3b, v201
	v_pk_mul_f32 v[2:3], v[2:3], v[172:173]
	v_pk_mul_f32 v[172:173], v[178:179], v[198:199]
	v_exp_f32_e32 v1, v1
	v_pk_mul_f32 v[46:47], v[46:47], v[172:173]
	v_max_f32_e64 v172, -v206, -v206
	v_min_f32_e32 v172, 0x42a00000, v172
	v_mul_f32_e32 v172, 0x3fb8aa3b, v172
	v_exp_f32_e32 v203, v172
	v_add_f32_e32 v1, 1.0, v1
	v_rcp_f32_e32 v201, v1
	v_lshlrev_b32_e32 v1, 16, v168
	v_mul_f32_e32 v1, 0xbfb8aa3b, v1
	v_pk_mul_f32 v[44:45], v[44:45], v[2:3]
	v_pk_add_f32 v[2:3], v[202:203], 1.0 op_sel_hi:[1,0]
	v_exp_f32_e32 v1, v1
	v_pk_add_f32 v[172:173], v[176:177], 1.0 op_sel_hi:[1,0]
	v_pk_mul_f32 v[2:3], v[200:201], v[2:3]
	v_pk_mul_f32 v[172:173], v[174:175], v[172:173]
	v_pk_mul_f32 v[50:51], v[50:51], v[2:3]
	v_and_b32_e32 v3, 0xffff0000, v168
	v_lshlrev_b32_e32 v168, 16, v170
	v_pk_mul_f32 v[48:49], v[48:49], v[172:173]
	v_lshlrev_b32_e32 v172, 16, v169
	v_and_b32_e32 v173, 0xffff0000, v169
	v_and_b32_e32 v169, 0xffff0000, v170
	v_lshlrev_b32_e32 v174, 16, v171
	v_and_b32_e32 v175, 0xffff0000, v171
	v_lshlrev_b32_e32 v170, 16, v164
	v_and_b32_e32 v171, 0xffff0000, v164
	v_mul_f32_e32 v164, 0xbfb8aa3b, v168
	v_lshlrev_b32_e32 v176, 16, v165
	v_and_b32_e32 v177, 0xffff0000, v165
	v_lshlrev_b32_e32 v165, 16, v166
	v_and_b32_e32 v178, 0xffff0000, v166
	v_add_f32_e32 v1, 1.0, v1
	v_exp_f32_e32 v166, v164
	v_rcp_f32_e32 v2, v1
	v_max_f32_e64 v1, -v170, -v170
	v_min_f32_e32 v1, 0x42a00000, v1
	v_mul_f32_e32 v1, 0x3fb8aa3b, v1
	v_mul_f32_e32 v3, 0xbfb8aa3b, v3
	v_exp_f32_e32 v164, v1
	v_add_f32_e32 v1, 1.0, v166
	v_exp_f32_e32 v3, v3
	v_rcp_f32_e32 v166, v1
	v_max_f32_e64 v1, -v165, -v165
	v_min_f32_e32 v1, 0x42a00000, v1
	v_mul_f32_e32 v1, 0x3fb8aa3b, v1
	v_mul_f32_e32 v165, 0xbfb8aa3b, v169
	v_lshlrev_b32_e32 v179, 16, v167
	v_and_b32_e32 v198, 0xffff0000, v167
	v_exp_f32_e32 v168, v1
	v_add_f32_e32 v1, 1.0, v3
	v_exp_f32_e32 v167, v165
	v_rcp_f32_e32 v3, v1
	v_max_f32_e64 v1, -v171, -v171
	v_min_f32_e32 v1, 0x42a00000, v1
	v_mul_f32_e32 v1, 0x3fb8aa3b, v1
	v_mul_f32_e32 v169, 0xbfb8aa3b, v172
	v_exp_f32_e32 v165, v1
	v_add_f32_e32 v1, 1.0, v167
	v_exp_f32_e32 v170, v169
	v_rcp_f32_e32 v167, v1
	v_max_f32_e64 v1, -v178, -v178
	v_min_f32_e32 v1, 0x42a00000, v1
	v_mul_f32_e32 v1, 0x3fb8aa3b, v1
	v_mul_f32_e32 v171, 0xbfb8aa3b, v174
	v_exp_f32_e32 v169, v1
	v_add_f32_e32 v1, 1.0, v170
	v_exp_f32_e32 v171, v171
	v_rcp_f32_e32 v170, v1
	v_max_f32_e64 v1, -v176, -v176
	v_min_f32_e32 v1, 0x42a00000, v1
	v_mul_f32_e32 v1, 0x3fb8aa3b, v1
	v_exp_f32_e32 v172, v1
	v_add_f32_e32 v1, 1.0, v171
	v_mul_f32_e32 v171, 0xbfb8aa3b, v173
	v_exp_f32_e32 v171, v171
	v_rcp_f32_e32 v174, v1
	v_max_f32_e64 v1, -v179, -v179
	v_max_f32_e64 v173, -v177, -v177
	v_min_f32_e32 v1, 0x42a00000, v1
	v_min_f32_e32 v173, 0x42a00000, v173
	v_mul_f32_e32 v1, 0x3fb8aa3b, v1
	v_mul_f32_e32 v173, 0x3fb8aa3b, v173
	v_exp_f32_e32 v173, v173
	v_exp_f32_e32 v176, v1
	v_add_f32_e32 v1, 1.0, v171
	v_rcp_f32_e32 v171, v1
	v_pk_add_f32 v[172:173], v[172:173], 1.0 op_sel_hi:[1,0]
	v_pk_add_f32 v[164:165], v[164:165], 1.0 op_sel_hi:[1,0]
	v_mul_f32_e32 v1, 0xbfb8aa3b, v175
	v_pk_mul_f32 v[2:3], v[2:3], v[164:165]
	v_pk_mul_f32 v[164:165], v[170:171], v[172:173]
	v_exp_f32_e32 v1, v1
	v_pk_mul_f32 v[38:39], v[38:39], v[164:165]
	v_max_f32_e64 v164, -v198, -v198
	v_min_f32_e32 v164, 0x42a00000, v164
	v_mul_f32_e32 v164, 0x3fb8aa3b, v164
	v_exp_f32_e32 v177, v164
	v_add_f32_e32 v1, 1.0, v1
	v_rcp_f32_e32 v175, v1
	v_lshlrev_b32_e32 v1, 16, v160
	v_mul_f32_e32 v1, 0xbfb8aa3b, v1
	v_pk_mul_f32 v[36:37], v[36:37], v[2:3]
	v_pk_add_f32 v[2:3], v[176:177], 1.0 op_sel_hi:[1,0]
	v_exp_f32_e32 v1, v1
	v_pk_add_f32 v[164:165], v[168:169], 1.0 op_sel_hi:[1,0]
	v_pk_mul_f32 v[2:3], v[174:175], v[2:3]
	v_pk_mul_f32 v[164:165], v[166:167], v[164:165]
	v_pk_mul_f32 v[42:43], v[42:43], v[2:3]
	v_and_b32_e32 v3, 0xffff0000, v160
	v_lshlrev_b32_e32 v160, 16, v162
	v_pk_mul_f32 v[40:41], v[40:41], v[164:165]
	v_lshlrev_b32_e32 v164, 16, v161
	v_and_b32_e32 v165, 0xffff0000, v161
	v_and_b32_e32 v161, 0xffff0000, v162
	v_lshlrev_b32_e32 v166, 16, v163
	v_and_b32_e32 v167, 0xffff0000, v163
	v_lshlrev_b32_e32 v162, 16, v156
	v_and_b32_e32 v163, 0xffff0000, v156
	v_mul_f32_e32 v156, 0xbfb8aa3b, v160
	v_lshlrev_b32_e32 v168, 16, v157
	v_and_b32_e32 v169, 0xffff0000, v157
	v_lshlrev_b32_e32 v157, 16, v158
	v_and_b32_e32 v170, 0xffff0000, v158
	v_add_f32_e32 v1, 1.0, v1
	v_exp_f32_e32 v158, v156
	v_rcp_f32_e32 v2, v1
	v_max_f32_e64 v1, -v162, -v162
	v_min_f32_e32 v1, 0x42a00000, v1
	v_mul_f32_e32 v1, 0x3fb8aa3b, v1
	v_mul_f32_e32 v3, 0xbfb8aa3b, v3
	v_exp_f32_e32 v156, v1
	v_add_f32_e32 v1, 1.0, v158
	v_exp_f32_e32 v3, v3
	v_rcp_f32_e32 v158, v1
	v_max_f32_e64 v1, -v157, -v157
	v_min_f32_e32 v1, 0x42a00000, v1
	v_mul_f32_e32 v1, 0x3fb8aa3b, v1
	v_mul_f32_e32 v157, 0xbfb8aa3b, v161
	v_lshlrev_b32_e32 v171, 16, v159
	v_and_b32_e32 v172, 0xffff0000, v159
	v_exp_f32_e32 v160, v1
	v_add_f32_e32 v1, 1.0, v3
	v_exp_f32_e32 v159, v157
	v_rcp_f32_e32 v3, v1
	v_max_f32_e64 v1, -v163, -v163
	v_min_f32_e32 v1, 0x42a00000, v1
	v_mul_f32_e32 v1, 0x3fb8aa3b, v1
	v_mul_f32_e32 v161, 0xbfb8aa3b, v164
	v_exp_f32_e32 v157, v1
	v_add_f32_e32 v1, 1.0, v159
	v_exp_f32_e32 v162, v161
	v_rcp_f32_e32 v159, v1
	v_max_f32_e64 v1, -v170, -v170
	v_min_f32_e32 v1, 0x42a00000, v1
	v_mul_f32_e32 v1, 0x3fb8aa3b, v1
	v_mul_f32_e32 v163, 0xbfb8aa3b, v166
	v_exp_f32_e32 v161, v1
	v_add_f32_e32 v1, 1.0, v162
	v_exp_f32_e32 v163, v163
	v_rcp_f32_e32 v162, v1
	v_max_f32_e64 v1, -v168, -v168
	v_min_f32_e32 v1, 0x42a00000, v1
	v_mul_f32_e32 v1, 0x3fb8aa3b, v1
	v_exp_f32_e32 v164, v1
	v_add_f32_e32 v1, 1.0, v163
	v_mul_f32_e32 v163, 0xbfb8aa3b, v165
	v_exp_f32_e32 v163, v163
	v_rcp_f32_e32 v166, v1
	v_max_f32_e64 v1, -v171, -v171
	v_max_f32_e64 v165, -v169, -v169
	v_min_f32_e32 v1, 0x42a00000, v1
	v_min_f32_e32 v165, 0x42a00000, v165
	v_mul_f32_e32 v1, 0x3fb8aa3b, v1
	v_mul_f32_e32 v165, 0x3fb8aa3b, v165
	v_exp_f32_e32 v165, v165
	v_exp_f32_e32 v168, v1
	v_add_f32_e32 v1, 1.0, v163
	v_rcp_f32_e32 v163, v1
	v_pk_add_f32 v[164:165], v[164:165], 1.0 op_sel_hi:[1,0]
	v_pk_add_f32 v[156:157], v[156:157], 1.0 op_sel_hi:[1,0]
	v_mul_f32_e32 v1, 0xbfb8aa3b, v167
	v_pk_mul_f32 v[2:3], v[2:3], v[156:157]
	v_pk_mul_f32 v[156:157], v[162:163], v[164:165]
	v_exp_f32_e32 v1, v1
	v_pk_mul_f32 v[30:31], v[30:31], v[156:157]
	v_max_f32_e64 v156, -v172, -v172
	v_min_f32_e32 v156, 0x42a00000, v156
	v_mul_f32_e32 v156, 0x3fb8aa3b, v156
	v_exp_f32_e32 v169, v156
	v_add_f32_e32 v1, 1.0, v1
	v_rcp_f32_e32 v167, v1
	v_lshlrev_b32_e32 v1, 16, v152
	v_mul_f32_e32 v1, 0xbfb8aa3b, v1
	v_pk_mul_f32 v[28:29], v[28:29], v[2:3]
	v_pk_add_f32 v[2:3], v[168:169], 1.0 op_sel_hi:[1,0]
	v_exp_f32_e32 v1, v1
	v_pk_add_f32 v[156:157], v[160:161], 1.0 op_sel_hi:[1,0]
	v_pk_mul_f32 v[2:3], v[166:167], v[2:3]
	v_pk_mul_f32 v[156:157], v[158:159], v[156:157]
	v_pk_mul_f32 v[34:35], v[34:35], v[2:3]
	v_and_b32_e32 v3, 0xffff0000, v152
	v_lshlrev_b32_e32 v152, 16, v154
	v_pk_mul_f32 v[32:33], v[32:33], v[156:157]
	v_lshlrev_b32_e32 v156, 16, v153
	v_and_b32_e32 v157, 0xffff0000, v153
	v_and_b32_e32 v153, 0xffff0000, v154
	v_lshlrev_b32_e32 v158, 16, v155
	v_and_b32_e32 v159, 0xffff0000, v155
	v_lshlrev_b32_e32 v154, 16, v148
	v_and_b32_e32 v155, 0xffff0000, v148
	v_mul_f32_e32 v148, 0xbfb8aa3b, v152
	v_lshlrev_b32_e32 v160, 16, v149
	v_and_b32_e32 v161, 0xffff0000, v149
	v_lshlrev_b32_e32 v149, 16, v150
	v_and_b32_e32 v162, 0xffff0000, v150
	v_add_f32_e32 v1, 1.0, v1
	v_exp_f32_e32 v150, v148
	v_rcp_f32_e32 v2, v1
	v_max_f32_e64 v1, -v154, -v154
	v_min_f32_e32 v1, 0x42a00000, v1
	v_mul_f32_e32 v1, 0x3fb8aa3b, v1
	v_mul_f32_e32 v3, 0xbfb8aa3b, v3
	v_exp_f32_e32 v148, v1
	v_add_f32_e32 v1, 1.0, v150
	v_exp_f32_e32 v3, v3
	v_rcp_f32_e32 v150, v1
	v_max_f32_e64 v1, -v149, -v149
	v_min_f32_e32 v1, 0x42a00000, v1
	v_mul_f32_e32 v1, 0x3fb8aa3b, v1
	v_mul_f32_e32 v149, 0xbfb8aa3b, v153
	v_lshlrev_b32_e32 v163, 16, v151
	v_and_b32_e32 v164, 0xffff0000, v151
	v_exp_f32_e32 v152, v1
	v_add_f32_e32 v1, 1.0, v3
	v_exp_f32_e32 v151, v149
	v_rcp_f32_e32 v3, v1
	v_max_f32_e64 v1, -v155, -v155
	v_min_f32_e32 v1, 0x42a00000, v1
	v_mul_f32_e32 v1, 0x3fb8aa3b, v1
	v_mul_f32_e32 v153, 0xbfb8aa3b, v156
	v_exp_f32_e32 v149, v1
	v_add_f32_e32 v1, 1.0, v151
	v_exp_f32_e32 v154, v153
	v_rcp_f32_e32 v151, v1
	v_max_f32_e64 v1, -v162, -v162
	v_min_f32_e32 v1, 0x42a00000, v1
	v_mul_f32_e32 v1, 0x3fb8aa3b, v1
	v_mul_f32_e32 v155, 0xbfb8aa3b, v158
	v_exp_f32_e32 v153, v1
	v_add_f32_e32 v1, 1.0, v154
	v_exp_f32_e32 v155, v155
	v_rcp_f32_e32 v154, v1
	v_max_f32_e64 v1, -v160, -v160
	v_min_f32_e32 v1, 0x42a00000, v1
	v_mul_f32_e32 v1, 0x3fb8aa3b, v1
	v_exp_f32_e32 v156, v1
	v_add_f32_e32 v1, 1.0, v155
	v_mul_f32_e32 v155, 0xbfb8aa3b, v157
	v_exp_f32_e32 v155, v155
	v_rcp_f32_e32 v158, v1
	v_max_f32_e64 v1, -v163, -v163
	v_max_f32_e64 v157, -v161, -v161
	v_min_f32_e32 v1, 0x42a00000, v1
	v_min_f32_e32 v157, 0x42a00000, v157
	v_mul_f32_e32 v1, 0x3fb8aa3b, v1
	v_mul_f32_e32 v157, 0x3fb8aa3b, v157
	v_exp_f32_e32 v157, v157
	v_exp_f32_e32 v160, v1
	v_add_f32_e32 v1, 1.0, v155
	v_rcp_f32_e32 v155, v1
	v_pk_add_f32 v[156:157], v[156:157], 1.0 op_sel_hi:[1,0]
	v_pk_add_f32 v[148:149], v[148:149], 1.0 op_sel_hi:[1,0]
	v_mul_f32_e32 v1, 0xbfb8aa3b, v159
	v_pk_mul_f32 v[2:3], v[2:3], v[148:149]
	v_pk_mul_f32 v[148:149], v[154:155], v[156:157]
	v_exp_f32_e32 v1, v1
	v_pk_mul_f32 v[22:23], v[22:23], v[148:149]
	v_max_f32_e64 v148, -v164, -v164
	v_min_f32_e32 v148, 0x42a00000, v148
	v_mul_f32_e32 v148, 0x3fb8aa3b, v148
	v_exp_f32_e32 v161, v148
	v_add_f32_e32 v1, 1.0, v1
	v_rcp_f32_e32 v159, v1
	s_waitcnt vmcnt(0)
	v_lshlrev_b32_e32 v1, 16, v144
	v_mul_f32_e32 v1, 0xbfb8aa3b, v1
	v_pk_mul_f32 v[20:21], v[20:21], v[2:3]
	v_pk_add_f32 v[2:3], v[160:161], 1.0 op_sel_hi:[1,0]
	v_exp_f32_e32 v1, v1
	v_pk_add_f32 v[148:149], v[152:153], 1.0 op_sel_hi:[1,0]
	v_pk_mul_f32 v[2:3], v[158:159], v[2:3]
	v_pk_mul_f32 v[148:149], v[150:151], v[148:149]
	v_pk_mul_f32 v[26:27], v[26:27], v[2:3]
	v_and_b32_e32 v3, 0xffff0000, v144
	v_lshlrev_b32_e32 v144, 16, v146
	v_pk_mul_f32 v[24:25], v[24:25], v[148:149]
	v_lshlrev_b32_e32 v148, 16, v145
	v_and_b32_e32 v149, 0xffff0000, v145
	v_and_b32_e32 v145, 0xffff0000, v146
	v_lshlrev_b32_e32 v150, 16, v147
	v_and_b32_e32 v151, 0xffff0000, v147
	v_lshlrev_b32_e32 v146, 16, v140
	v_and_b32_e32 v147, 0xffff0000, v140
	v_mul_f32_e32 v140, 0xbfb8aa3b, v144
	v_lshlrev_b32_e32 v152, 16, v141
	v_and_b32_e32 v153, 0xffff0000, v141
	v_lshlrev_b32_e32 v141, 16, v142
	v_and_b32_e32 v154, 0xffff0000, v142
	v_add_f32_e32 v1, 1.0, v1
	v_exp_f32_e32 v142, v140
	v_rcp_f32_e32 v2, v1
	v_max_f32_e64 v1, -v146, -v146
	v_min_f32_e32 v1, 0x42a00000, v1
	v_mul_f32_e32 v1, 0x3fb8aa3b, v1
	v_mul_f32_e32 v3, 0xbfb8aa3b, v3
	v_exp_f32_e32 v140, v1
	v_add_f32_e32 v1, 1.0, v142
	v_exp_f32_e32 v3, v3
	v_rcp_f32_e32 v142, v1
	v_max_f32_e64 v1, -v141, -v141
	v_min_f32_e32 v1, 0x42a00000, v1
	v_mul_f32_e32 v1, 0x3fb8aa3b, v1
	v_mul_f32_e32 v141, 0xbfb8aa3b, v145
	v_lshlrev_b32_e32 v155, 16, v143
	v_and_b32_e32 v156, 0xffff0000, v143
	v_exp_f32_e32 v144, v1
	v_add_f32_e32 v1, 1.0, v3
	v_exp_f32_e32 v143, v141
	v_rcp_f32_e32 v3, v1
	v_max_f32_e64 v1, -v147, -v147
	v_min_f32_e32 v1, 0x42a00000, v1
	v_mul_f32_e32 v1, 0x3fb8aa3b, v1
	v_mul_f32_e32 v145, 0xbfb8aa3b, v148
	v_exp_f32_e32 v141, v1
	v_add_f32_e32 v1, 1.0, v143
	v_exp_f32_e32 v146, v145
	v_rcp_f32_e32 v143, v1
	v_max_f32_e64 v1, -v154, -v154
	v_min_f32_e32 v1, 0x42a00000, v1
	v_mul_f32_e32 v1, 0x3fb8aa3b, v1
	v_mul_f32_e32 v147, 0xbfb8aa3b, v150
	v_exp_f32_e32 v145, v1
	v_add_f32_e32 v1, 1.0, v146
	v_exp_f32_e32 v147, v147
	v_rcp_f32_e32 v146, v1
	v_max_f32_e64 v1, -v152, -v152
	v_min_f32_e32 v1, 0x42a00000, v1
	v_mul_f32_e32 v1, 0x3fb8aa3b, v1
	v_exp_f32_e32 v148, v1
	v_add_f32_e32 v1, 1.0, v147
	v_mul_f32_e32 v147, 0xbfb8aa3b, v149
	v_exp_f32_e32 v147, v147
	v_rcp_f32_e32 v150, v1
	v_max_f32_e64 v1, -v155, -v155
	v_max_f32_e64 v149, -v153, -v153
	v_min_f32_e32 v1, 0x42a00000, v1
	v_min_f32_e32 v149, 0x42a00000, v149
	v_mul_f32_e32 v1, 0x3fb8aa3b, v1
	v_mul_f32_e32 v149, 0x3fb8aa3b, v149
	v_exp_f32_e32 v149, v149
	v_exp_f32_e32 v152, v1
	v_add_f32_e32 v1, 1.0, v147
	v_rcp_f32_e32 v147, v1
	v_pk_add_f32 v[148:149], v[148:149], 1.0 op_sel_hi:[1,0]
	v_pk_add_f32 v[140:141], v[140:141], 1.0 op_sel_hi:[1,0]
	v_mul_f32_e32 v1, 0xbfb8aa3b, v151
	v_pk_mul_f32 v[2:3], v[2:3], v[140:141]
	v_pk_mul_f32 v[140:141], v[146:147], v[148:149]
	v_exp_f32_e32 v1, v1
	v_pk_mul_f32 v[14:15], v[14:15], v[140:141]
	v_max_f32_e64 v140, -v156, -v156
	v_min_f32_e32 v140, 0x42a00000, v140
	v_mul_f32_e32 v140, 0x3fb8aa3b, v140
	v_exp_f32_e32 v153, v140
	v_add_f32_e32 v1, 1.0, v1
	v_rcp_f32_e32 v151, v1
	v_lshlrev_b32_e32 v1, 16, v136
	v_mul_f32_e32 v1, 0xbfb8aa3b, v1
	v_pk_mul_f32 v[12:13], v[12:13], v[2:3]
	v_pk_add_f32 v[2:3], v[152:153], 1.0 op_sel_hi:[1,0]
	v_exp_f32_e32 v1, v1
	v_pk_add_f32 v[140:141], v[144:145], 1.0 op_sel_hi:[1,0]
	v_pk_mul_f32 v[2:3], v[150:151], v[2:3]
	v_pk_mul_f32 v[140:141], v[142:143], v[140:141]
	v_pk_mul_f32 v[18:19], v[18:19], v[2:3]
	v_and_b32_e32 v3, 0xffff0000, v136
	v_lshlrev_b32_e32 v136, 16, v138
	v_pk_mul_f32 v[16:17], v[16:17], v[140:141]
	v_lshlrev_b32_e32 v140, 16, v137
	v_and_b32_e32 v141, 0xffff0000, v137
	v_and_b32_e32 v137, 0xffff0000, v138
	v_lshlrev_b32_e32 v142, 16, v139
	v_and_b32_e32 v143, 0xffff0000, v139
	v_lshlrev_b32_e32 v138, 16, v132
	v_and_b32_e32 v139, 0xffff0000, v132
	v_mul_f32_e32 v132, 0xbfb8aa3b, v136
	v_lshlrev_b32_e32 v144, 16, v133
	v_and_b32_e32 v145, 0xffff0000, v133
	v_lshlrev_b32_e32 v133, 16, v134
	v_and_b32_e32 v146, 0xffff0000, v134
	v_add_f32_e32 v1, 1.0, v1
	v_exp_f32_e32 v134, v132
	v_rcp_f32_e32 v2, v1
	v_max_f32_e64 v1, -v138, -v138
	v_min_f32_e32 v1, 0x42a00000, v1
	v_mul_f32_e32 v1, 0x3fb8aa3b, v1
	v_mul_f32_e32 v3, 0xbfb8aa3b, v3
	v_exp_f32_e32 v132, v1
	v_add_f32_e32 v1, 1.0, v134
	v_exp_f32_e32 v3, v3
	v_rcp_f32_e32 v134, v1
	v_max_f32_e64 v1, -v133, -v133
	v_min_f32_e32 v1, 0x42a00000, v1
	v_mul_f32_e32 v1, 0x3fb8aa3b, v1
	v_mul_f32_e32 v133, 0xbfb8aa3b, v137
	v_lshlrev_b32_e32 v147, 16, v135
	v_and_b32_e32 v148, 0xffff0000, v135
	v_exp_f32_e32 v136, v1
	v_add_f32_e32 v1, 1.0, v3
	v_exp_f32_e32 v135, v133
	v_rcp_f32_e32 v3, v1
	v_max_f32_e64 v1, -v139, -v139
	v_min_f32_e32 v1, 0x42a00000, v1
	v_mul_f32_e32 v1, 0x3fb8aa3b, v1
	v_mul_f32_e32 v137, 0xbfb8aa3b, v140
	v_exp_f32_e32 v133, v1
	v_add_f32_e32 v1, 1.0, v135
	v_exp_f32_e32 v138, v137
	v_rcp_f32_e32 v135, v1
	v_max_f32_e64 v1, -v146, -v146
	v_min_f32_e32 v1, 0x42a00000, v1
	v_mul_f32_e32 v1, 0x3fb8aa3b, v1
	v_mul_f32_e32 v139, 0xbfb8aa3b, v142
	v_exp_f32_e32 v137, v1
	v_add_f32_e32 v1, 1.0, v138
	v_exp_f32_e32 v139, v139
	v_rcp_f32_e32 v138, v1
	v_max_f32_e64 v1, -v144, -v144
	v_min_f32_e32 v1, 0x42a00000, v1
	v_mul_f32_e32 v1, 0x3fb8aa3b, v1
	v_exp_f32_e32 v140, v1
	v_add_f32_e32 v1, 1.0, v139
	v_mul_f32_e32 v139, 0xbfb8aa3b, v141
	v_exp_f32_e32 v139, v139
	v_rcp_f32_e32 v142, v1
	v_max_f32_e64 v1, -v147, -v147
	v_max_f32_e64 v141, -v145, -v145
	v_min_f32_e32 v1, 0x42a00000, v1
	v_min_f32_e32 v141, 0x42a00000, v141
	v_mul_f32_e32 v1, 0x3fb8aa3b, v1
	v_mul_f32_e32 v141, 0x3fb8aa3b, v141
	v_exp_f32_e32 v141, v141
	v_exp_f32_e32 v144, v1
	v_add_f32_e32 v1, 1.0, v139
	v_rcp_f32_e32 v139, v1
	v_pk_add_f32 v[140:141], v[140:141], 1.0 op_sel_hi:[1,0]
	v_pk_add_f32 v[132:133], v[132:133], 1.0 op_sel_hi:[1,0]
	v_mul_f32_e32 v1, 0xbfb8aa3b, v143
	v_pk_mul_f32 v[2:3], v[2:3], v[132:133]
	v_pk_mul_f32 v[132:133], v[138:139], v[140:141]
	v_exp_f32_e32 v1, v1
	v_pk_mul_f32 v[6:7], v[6:7], v[132:133]
	v_max_f32_e64 v132, -v148, -v148
	v_min_f32_e32 v132, 0x42a00000, v132
	v_mul_f32_e32 v132, 0x3fb8aa3b, v132
	v_exp_f32_e32 v145, v132
	v_add_f32_e32 v1, 1.0, v1
	v_rcp_f32_e32 v143, v1
	v_pk_mul_f32 v[4:5], v[4:5], v[2:3]
	v_pk_add_f32 v[2:3], v[144:145], 1.0 op_sel_hi:[1,0]
	v_pk_add_f32 v[132:133], v[136:137], 1.0 op_sel_hi:[1,0]
	v_pk_mul_f32 v[2:3], v[142:143], v[2:3]
	v_pk_mul_f32 v[132:133], v[134:135], v[132:133]
	v_pk_mul_f32 v[10:11], v[10:11], v[2:3]
	v_pk_mul_f32 v[8:9], v[8:9], v[132:133]
	s_branch .LBB0_678
